# v114 with the out-proj small-tile-first half chosen by XCD parity (bid bit 0) instead of bid bit 3: whole XCDs run their K-loops in lockstep
# baseline (speedup 1.0000x reference)
; #define FRESH_TID() int tid = threadIdx.x; asm volatile("" : "+v"(tid)); const int lane = tid & 63, wave = __builtin_amdgcn_readfirstlane(tid >> 6)
; __global__ void __launch_bounds__(512, 2) fwd_megakernel(Args a) {
;     ...
;             const bool small_first = ((bid >> 3) & 1) != 0;
; #pragma unroll 1
;             for (int step = 0; step < 2; ++step) {
;                 if ((step == 0) == small_first) { FRESH_TID();
;                     for (int t = bid; t < 256; t += G) g2_sample_tile((const bf16_t*)(a.ws + WS_H), (const bf16_t*)(a.ws + WS_WOUT) + (size_t)l * D * D, nullptr, XBase + (size_t)MP * D, a.out + (size_t)MP * D, l == 0 ? XB + (size_t)MP * D : nullptr, gate, lds, t, tid, lane, wave);
;                 } else {
;                     pg8::gemm_phase<pg8::EpiGate, pg8::StaticOrder, true, true>(lds, g, S, E);
;                 }
;             }
.LBB0_587:
	s_or_b64 exec, exec, s[0:1]
	s_lshl_b64 s[0:1], s[22:23], 21
	v_readlane_b32 s2, v254, 22
	s_add_u32 s2, s2, s0
	v_readlane_b32 s0, v254, 23
	s_addc_u32 s3, s0, s1
	v_readlane_b32 s0, v255, 10
	s_add_u32 s0, s78, s0
	s_addc_u32 s1, s79, 0
	s_add_u32 s4, s0, 0x1202000
	s_addc_u32 s5, s1, 0
	v_readlane_b32 s0, v255, 13
	v_readlane_b32 s1, v255, 14
	s_add_u32 s6, s78, s0
	s_addc_u32 s7, s79, s1
	s_bitcmp1_b32 s22, 0
	s_cselect_b64 s[0:1], -1, 0
	s_xor_b64 s[8:9], s[0:1], -1
	s_add_u32 s10, s6, 0x2000000
	s_addc_u32 s11, s7, 0
	v_readlane_b32 s0, v254, 29
	v_readlane_b32 s1, v254, 30
	s_add_u32 s14, s2, s0
	s_addc_u32 s15, s3, s1
	s_add_u32 s16, s14, 0x40000
	s_addc_u32 s17, s15, 0
	s_add_u32 s18, s14, 0x40080
	s_mov_b64 s[12:13], -1
	s_addc_u32 s19, s15, 0
	s_mov_b32 s0, 0
	s_waitcnt lgkmcnt(0)
	s_barrier
	s_cmp_lg_u32 s42, 0x100
	s_cbranch_scc1 .Lopo_skip
	s_bfe_u32 s85, s71, 0x10000
.Lopo_skip:
	s_branch .LBB0_590
.LBB0_588:
	s_waitcnt vmcnt(0)
	v_readlane_b32 s54, v254, 60
	v_readlane_b32 s56, v254, 62
	v_readlane_b32 s60, v255, 0
	v_readlane_b32 s62, v255, 2
	v_readlane_b32 s55, v254, 61
	v_readlane_b32 s57, v254, 63
	v_readlane_b32 s61, v255, 1
	v_readlane_b32 s63, v255, 3
	v_readlane_b32 s25, v254, 41
	v_readlane_b32 s28, v254, 43
	s_barrier
